# P.V section: block-transition lgkmcnt(0) waits moved behind the last MFMA of the previous block; block 2's last four V transpose reads issued before MFMA 8
# speedup vs baseline: 1.0063x; 1.0063x over previous
; #define MFMA32(a, b, c) __builtin_amdgcn_mfma_f32_32x32x16_bf16((a), (b), (c), 0, 0, 0)
; DI void a_finishSM(f32x16& p0, f32x16& p1, float alpha, float& l_reg, bf16x8& pa0, bf16x8& pa1, bf16x8& pa2, bf16x8& pa3) {
; #pragma unroll
;   for (int r = 0; r < 16; ++r) p1[r] = __builtin_amdgcn_exp2f(p1[r]);
;   float ps = 0;
; #pragma unroll
;   for (int r = 0; r < 16; ++r) ps += p0[r];
; #pragma unroll
;   for (int r = 0; r < 16; ++r) ps += p1[r];
;   { auto rr = __builtin_amdgcn_permlane32_swap(__float_as_uint(ps), __float_as_uint(ps), false, false);
;     ps = __uint_as_float(rr[0]) + __uint_as_float(rr[1]); }
;   l_reg = l_reg * alpha + ps;
;     ...
;   PK4(p0, 0, pa0); PK4(p0, 8, pa1); PK4(p1, 0, pa2); PK4(p1, 8, pa3);
;     ...
; }
; DI void a_qkt(f32x16& p0, f32x16& p1, const char* Ks, const char* Ps, const bf16x8* qr, const char* QP, int r32, int hi) {
;   p0 = f32x16{}; p1 = f32x16{};
; #pragma unroll
;   for (int d0 = 0; d0 < 8; ++d0) { const int cb = (d0 * 16 + hi * 8) * 2;
;     bf16x8 b0 = *reinterpret_cast<const bf16x8*>(Ks + KSWZ(r32, cb));
;     bf16x8 b1 = *reinterpret_cast<const bf16x8*>(Ks + KSWZ(32 + r32, cb));
;     p0 = MFMA32(b0, qr[d0], p0);
;     p1 = MFMA32(b1, qr[d0], p1); }
; #pragma unroll
;   for (int d0 = 0; d0 < 4; ++d0) { const int cb = (d0 * 16 + hi * 8) * 2;
;     bf16x8 b0 = *reinterpret_cast<const bf16x8*>(Ps + PSWZ(r32, cb));
;     bf16x8 b1 = *reinterpret_cast<const bf16x8*>(Ps + PSWZ(32 + r32, cb));
;     const bf16x8 qp = *reinterpret_cast<const bf16x8*>(QP + d0 * 1024);
;     p0 = MFMA32(b0, qp, p0);
;     p1 = MFMA32(b1, qp, p1); }
; }
.LBB0_665:
	s_mov_b32 s8, s4
	s_add_i32 s4, s7, 0
	v_add_u32_e32 v70, s4, v170
	ds_read_b128 v[66:69], v70 offset:16384
	ds_read_b128 v[82:85], v70 offset:24576
	v_add_u32_e32 v166, s4, v172
	ds_read_b128 v[202:205], v166 offset:16384
	ds_read_b128 v[206:209], v166 offset:24576
	s_waitcnt lgkmcnt(3)
	v_mfma_f32_32x32x16_bf16 v[66:81], v[66:69], v[114:117], 0
	v_exp_f32_e32 v185, v130
	v_exp_f32_e32 v186, v131
	s_waitcnt lgkmcnt(2)
	v_mfma_f32_32x32x16_bf16 v[82:97], v[82:85], v[114:117], 0
	v_add_u32_e32 v166, s4, v173
	ds_read_b128 v[214:217], v166 offset:16384
	ds_read_b128 v[218:221], v166 offset:24576
	v_exp_f32_e32 v187, v146
	v_exp_f32_e32 v188, v147
	s_waitcnt lgkmcnt(3)
	v_mfma_f32_32x32x16_bf16 v[66:81], v[202:205], v[118:121], v[66:81]
	v_exp_f32_e32 v189, v132
	v_exp_f32_e32 v190, v133
	s_waitcnt lgkmcnt(2)
	v_mfma_f32_32x32x16_bf16 v[82:97], v[206:209], v[118:121], v[82:97]
	v_add_u32_e32 v166, s4, v174
	ds_read_b128 v[202:205], v166 offset:16384
	ds_read_b128 v[206:209], v166 offset:24576
	v_exp_f32_e32 v191, v148
	v_exp_f32_e32 v192, v149
	s_waitcnt lgkmcnt(3)
	v_mfma_f32_32x32x16_bf16 v[66:81], v[214:217], v[126:129], v[66:81]
	v_exp_f32_e32 v193, v150
	v_add_f32_e32 v201, 0, v240
	v_add_f32_e32 v201, v241, v201
	s_waitcnt lgkmcnt(2)
	v_mfma_f32_32x32x16_bf16 v[82:97], v[218:221], v[126:129], v[82:97]
	v_add_u32_e32 v166, s4, v175
	ds_read_b128 v[214:217], v166 offset:16384
	ds_read_b128 v[218:221], v166 offset:24576
	v_exp_f32_e32 v194, v151
	v_add_f32_e32 v201, v242, v201
	v_add_f32_e32 v201, v243, v201
	s_waitcnt lgkmcnt(3)
	v_mfma_f32_32x32x16_bf16 v[66:81], v[202:205], v[122:125], v[66:81]
	v_exp_f32_e32 v195, v154
	v_add_f32_e32 v201, v244, v201
	v_add_f32_e32 v201, v245, v201
	s_waitcnt lgkmcnt(2)
	v_mfma_f32_32x32x16_bf16 v[82:97], v[206:209], v[122:125], v[82:97]
	v_add_u32_e32 v166, s4, v176
	ds_read_b128 v[202:205], v166 offset:16384
	ds_read_b128 v[206:209], v166 offset:24576
	v_exp_f32_e32 v196, v155
	v_add_f32_e32 v201, v246, v201
	v_add_f32_e32 v201, v247, v201
	s_waitcnt lgkmcnt(3)
	v_mfma_f32_32x32x16_bf16 v[66:81], v[214:217], v[110:113], v[66:81]
	v_exp_f32_e32 v197, v152
	v_add_f32_e32 v201, v248, v201
	v_add_f32_e32 v201, v249, v201
	s_waitcnt lgkmcnt(2)
	v_mfma_f32_32x32x16_bf16 v[82:97], v[218:221], v[110:113], v[82:97]
	v_add_u32_e32 v166, s4, v177
	ds_read_b128 v[214:217], v166 offset:16384
	ds_read_b128 v[218:221], v166 offset:24576
	v_exp_f32_e32 v198, v153
	v_add_f32_e32 v201, v250, v201
	v_add_f32_e32 v201, v251, v201
	s_waitcnt lgkmcnt(3)
	v_mfma_f32_32x32x16_bf16 v[66:81], v[202:205], v[106:109], v[66:81]
	v_exp_f32_e32 v199, v156
	v_add_f32_e32 v201, v252, v201
	v_add_f32_e32 v201, v253, v201
	s_waitcnt lgkmcnt(2)
	v_mfma_f32_32x32x16_bf16 v[82:97], v[206:209], v[106:109], v[82:97]
	v_add_u32_e32 v166, s4, v178
	ds_read_b128 v[202:205], v166 offset:16384
	ds_read_b128 v[206:209], v166 offset:24576
	v_exp_f32_e32 v200, v157
	v_add_f32_e32 v201, v254, v201
	v_add_f32_e32 v201, v255, v201
	s_waitcnt lgkmcnt(3)
	v_mfma_f32_32x32x16_bf16 v[66:81], v[214:217], v[102:105], v[66:81]
	v_add_f32_e32 v201, v185, v201
	v_add_f32_e32 v201, v186, v201
	v_cvt_pk_bf16_f32 v130, v240, v241
	s_waitcnt lgkmcnt(2)
	v_mfma_f32_32x32x16_bf16 v[82:97], v[218:221], v[102:105], v[82:97]
	v_add_u32_e32 v166, s4, v179
	ds_read_b128 v[214:217], v166 offset:32768
	ds_read_b128 v[218:221], v166 offset:36864
	ds_read_b128 v[222:225], v163
	v_add_f32_e32 v201, v187, v201
	v_add_f32_e32 v201, v188, v201
	v_cvt_pk_bf16_f32 v131, v242, v243
	s_waitcnt lgkmcnt(4)
	v_mfma_f32_32x32x16_bf16 v[66:81], v[202:205], v[98:101], v[66:81]
	v_add_f32_e32 v201, v189, v201
	v_add_f32_e32 v201, v190, v201
	v_cvt_pk_bf16_f32 v132, v244, v245
	s_waitcnt lgkmcnt(3)
	v_mfma_f32_32x32x16_bf16 v[82:97], v[206:209], v[98:101], v[82:97]
	v_add_u32_e32 v166, s4, v180
	ds_read_b128 v[202:205], v166 offset:32768
	ds_read_b128 v[206:209], v166 offset:36864
	ds_read_b128 v[210:213], v163 offset:1024
	v_add_f32_e32 v201, v191, v201
	v_add_f32_e32 v201, v192, v201
	v_cvt_pk_bf16_f32 v133, v246, v247
	s_waitcnt lgkmcnt(3)
	v_mfma_f32_32x32x16_bf16 v[66:81], v[214:217], v[222:225], v[66:81]
	v_add_f32_e32 v201, v193, v201
	v_add_f32_e32 v201, v194, v201
	v_cvt_pk_bf16_f32 v154, v248, v249
	v_mfma_f32_32x32x16_bf16 v[82:97], v[218:221], v[222:225], v[82:97]
	v_add_u32_e32 v166, s4, v181
	ds_read_b128 v[214:217], v166 offset:32768
	ds_read_b128 v[218:221], v166 offset:36864
	ds_read_b128 v[222:225], v163 offset:2048
	v_add_f32_e32 v201, v195, v201
	v_add_f32_e32 v201, v196, v201
	v_cvt_pk_bf16_f32 v155, v250, v251
	s_waitcnt lgkmcnt(3)
	v_mfma_f32_32x32x16_bf16 v[66:81], v[202:205], v[210:213], v[66:81]
	v_add_f32_e32 v201, v197, v201
	v_add_f32_e32 v201, v198, v201
	v_cvt_pk_bf16_f32 v156, v252, v253
	v_mfma_f32_32x32x16_bf16 v[82:97], v[206:209], v[210:213], v[82:97]
	v_add_u32_e32 v166, s4, v182
	ds_read_b128 v[202:205], v166 offset:32768
	ds_read_b128 v[206:209], v166 offset:36864
	ds_read_b128 v[210:213], v163 offset:3072
	v_add_f32_e32 v201, v199, v201
	v_add_f32_e32 v150, v200, v201
	v_cvt_pk_bf16_f32 v157, v254, v255
	s_waitcnt lgkmcnt(3)
	v_mfma_f32_32x32x16_bf16 v[66:81], v[214:217], v[222:225], v[66:81]
	v_mov_b32_e32 v151, v150
	v_cvt_pk_bf16_f32 v184, v185, v186
	v_cvt_pk_bf16_f32 v185, v187, v188
	v_permlane32_swap_b32_e32 v130, v132
	v_mfma_f32_32x32x16_bf16 v[82:97], v[218:221], v[222:225], v[82:97]
	v_add_u32_e32 v166, s8, v171
	ds_read_b64_tr_b16 v[214:215], v166 offset:2048
	ds_read_b64_tr_b16 v[216:217], v166 offset:4096
	ds_read_b64_tr_b16 v[218:219], v166 offset:6144
	ds_read_b64_tr_b16 v[220:221], v166 offset:8192
	ds_read_b64_tr_b16 v[222:223], v166 offset:10240
	ds_read_b64_tr_b16 v[224:225], v166 offset:12288
	ds_read_b64_tr_b16 v[226:227], v166 offset:14336
	v_cvt_pk_bf16_f32 v186, v189, v190
	v_cvt_pk_bf16_f32 v187, v191, v192
	v_permlane32_swap_b32_e32 v150, v151
	v_permlane32_swap_b32_e32 v131, v133
	s_waitcnt lgkmcnt(7)
; DI void pv_sm(f32x16* o, int vb, bf16x8 pa0, bf16x8 pa1, bf16x8 pa2, bf16x8 pa3, f32x16& p0, f32x16& p1, float& m_reg, float& mn, float& alpha) {
;   PV_BLOCK(0)
;   float pm0 = p0[0];
; #pragma unroll
;   for (int r = 1; r < 16; ++r) pm0 = fmaxf(pm0, p0[r]);
;   PV_BLOCK(1)
;   float pmax = pm0;
; #pragma unroll
;   for (int r = 0; r < 16; ++r) pmax = fmaxf(pmax, p1[r]);
;   { auto rr = __builtin_amdgcn_permlane32_swap(__float_as_uint(pmax), __float_as_uint(pmax), false, false);
;     pmax = fmaxf(__uint_as_float(rr[0]), __uint_as_float(rr[1])); }
;   const bool keep = __all(pmax - m_reg <= ATH);
;   mn = keep ? m_reg : fmaxf(m_reg, pmax);
;   alpha = __builtin_amdgcn_exp2f(m_reg - mn);
;   m_reg = mn;
;   PV_BLOCK(2)
; #pragma unroll
;   for (int r = 0; r < 16; ++r) { p0[r] = p0[r] - mn; p1[r] = p1[r] - mn; }
;   PV_BLOCK(3)
; #pragma unroll
;   for (int r = 0; r < 16; ++r) p0[r] = __builtin_amdgcn_exp2f(p0[r]);
; }
	v_mfma_f32_32x32x16_bf16 v[66:81], v[202:205], v[210:213], v[66:81]
	v_cvt_pk_bf16_f32 v188, v193, v194
	v_cvt_pk_bf16_f32 v189, v195, v196
	v_permlane32_swap_b32_e32 v154, v156
	v_mfma_f32_32x32x16_bf16 v[82:97], v[206:209], v[210:213], v[82:97]
	ds_read_b64_tr_b16 v[212:213], v166 offset:0
	v_cvt_pk_bf16_f32 v190, v197, v198
	v_cvt_pk_bf16_f32 v191, v199, v200
	v_permlane32_swap_b32_e32 v155, v157
	s_nop 0
	v_permlane32_swap_b32_e32 v184, v186
	v_permlane32_swap_b32_e32 v185, v187
	v_permlane32_swap_b32_e32 v188, v190
	v_permlane32_swap_b32_e32 v189, v191
	v_lshl_add_u64 v[146:147], s[84:85], 0, v[142:143]
	v_add_co_u32_e32 v148, vcc, s56, v146
	s_nop 1
	v_addc_co_u32_e32 v149, vcc, 0, v147, vcc
	v_add_co_u32_e32 v152, vcc, s57, v146
	s_nop 1
	v_addc_co_u32_e32 v153, vcc, 0, v147, vcc
	global_load_dwordx4 v[192:195], v[148:149], off offset:256
	global_load_dwordx4 v[196:199], v[148:149], off
	global_load_dwordx4 v[200:203], v[152:153], off offset:256
	global_load_dwordx4 v[204:207], v[152:153], off
	v_lshl_add_u64 v[148:149], s[84:85], 0, v[140:141]
	v_add_co_u32_e32 v152, vcc, s58, v148
	s_nop 1
	v_addc_co_u32_e32 v153, vcc, 0, v149, vcc
	global_load_dwordx4 v[208:211], v[152:153], off
	v_add_u32_e32 v166, s8, v171
	s_waitcnt lgkmcnt(0)
	s_nop 0
	v_mfma_f32_32x32x16_bf16 v[2:17], v[130:133], v[212:215], v[2:17]
	ds_read_b64_tr_b16 v[212:213], v166 offset:0x200
	ds_read_b64_tr_b16 v[214:215], v166 offset:0xa00
	v_max_f32_e32 v152, v67, v67
	v_max_f32_e32 v153, v66, v66
	v_max_f32_e32 v152, v153, v152
	v_max3_f32 v152, v152, v68, v69
	v_max3_f32 v152, v152, v70, v71
	v_mfma_f32_32x32x16_bf16 v[2:17], v[154:157], v[216:219], v[2:17]
	ds_read_b64_tr_b16 v[216:217], v166 offset:0x1200
	ds_read_b64_tr_b16 v[218:219], v166 offset:0x1a00
	v_max3_f32 v152, v152, v72, v73
	v_max3_f32 v152, v152, v74, v75
	v_max3_f32 v152, v152, v76, v77
	v_max3_f32 v152, v152, v78, v79
	v_max3_f32 v152, v152, v80, v81
	v_mfma_f32_32x32x16_bf16 v[2:17], v[184:187], v[220:223], v[2:17]
	ds_read_b64_tr_b16 v[220:221], v166 offset:0x2200
	ds_read_b64_tr_b16 v[222:223], v166 offset:0x2a00
	ds_read_b64_tr_b16 v[228:229], v166 offset:0x3200
	ds_read_b64_tr_b16 v[230:231], v166 offset:0x3a00
	v_mfma_f32_32x32x16_bf16 v[2:17], v[188:191], v[224:227], v[2:17]
	s_waitcnt lgkmcnt(0)
	v_mfma_f32_32x32x16_bf16 v[50:65], v[130:133], v[212:215], v[50:65]
	v_max3_f32 v152, v152, v82, v83
	v_max3_f32 v152, v152, v84, v85
	v_max3_f32 v152, v152, v86, v87
	v_max3_f32 v152, v152, v88, v89
	v_max3_f32 v152, v152, v90, v91
	v_max3_f32 v152, v152, v92, v93
	v_max3_f32 v152, v152, v94, v95
	v_mfma_f32_32x32x16_bf16 v[50:65], v[154:157], v[216:219], v[50:65]
	v_max3_f32 v152, v152, v96, v97
	v_mov_b32_e32 v153, v152
	s_nop 1
	v_permlane32_swap_b32_e32 v152, v153
	v_max_f32_e32 v153, v153, v153
	v_max_f32_e32 v152, v152, v152
	v_max_f32_e32 v152, v152, v153
	v_mfma_f32_32x32x16_bf16 v[50:65], v[184:187], v[220:223], v[50:65]
	ds_read_b64_tr_b16 v[212:213], v166 offset:0x400
	v_sub_f32_e32 v153, v152, v144
	ds_read_b64_tr_b16 v[214:215], v166 offset:0xc00
	v_cmp_ge_f32_e32 vcc, s54, v153
	ds_read_b64_tr_b16 v[216:217], v166 offset:0x1400
	s_cmp_eq_u64 vcc, exec
	v_max_f32_e32 v153, v144, v144
	ds_read_b64_tr_b16 v[218:219], v166 offset:0x1c00
	ds_read_b64_tr_b16 v[220:221], v166 offset:0x2400
	ds_read_b64_tr_b16 v[222:223], v166 offset:0x2c00
	ds_read_b64_tr_b16 v[224:225], v166 offset:0x3400
	ds_read_b64_tr_b16 v[226:227], v166 offset:0x3c00
	v_mfma_f32_32x32x16_bf16 v[50:65], v[188:191], v[228:231], v[50:65]
	v_max_f32_e32 v152, v153, v152
	s_cselect_b64 vcc, -1, 0
	v_cndmask_b32_e32 v153, v152, v144, vcc
	v_sub_f32_e32 v144, v144, v153
	v_exp_f32_e32 v152, v144
	s_waitcnt lgkmcnt(0)
	v_mfma_f32_32x32x16_bf16 v[34:49], v[130:133], v[212:215], v[34:49]
	ds_read_b64_tr_b16 v[212:213], v166 offset:0x600
	ds_read_b64_tr_b16 v[214:215], v166 offset:0xe00
	v_sub_f32_e32 v66, v66, v153
	v_sub_f32_e32 v67, v67, v153
	v_sub_f32_e32 v68, v68, v153
	v_sub_f32_e32 v69, v69, v153
	v_mfma_f32_32x32x16_bf16 v[34:49], v[154:157], v[216:219], v[34:49]
	ds_read_b64_tr_b16 v[216:217], v166 offset:0x1600
	ds_read_b64_tr_b16 v[218:219], v166 offset:0x1e00
	v_sub_f32_e32 v70, v70, v153
	v_sub_f32_e32 v71, v71, v153
	v_exp_f32_e32 v240, v66
	v_exp_f32_e32 v241, v67
	v_mfma_f32_32x32x16_bf16 v[34:49], v[184:187], v[220:223], v[34:49]
	ds_read_b64_tr_b16 v[220:221], v166 offset:0x2600
	ds_read_b64_tr_b16 v[222:223], v166 offset:0x2e00
	ds_read_b64_tr_b16 v[228:229], v166 offset:0x3600
	ds_read_b64_tr_b16 v[230:231], v166 offset:0x3e00
	v_mfma_f32_32x32x16_bf16 v[34:49], v[188:191], v[224:227], v[34:49]
	v_sub_f32_e32 v72, v72, v153
	v_sub_f32_e32 v73, v73, v153
	v_exp_f32_e32 v242, v68
	v_exp_f32_e32 v243, v69
	s_waitcnt lgkmcnt(0)
	v_sub_f32_e32 v74, v74, v153
	v_sub_f32_e32 v75, v75, v153
	v_exp_f32_e32 v244, v70
	v_exp_f32_e32 v245, v71
	v_mfma_f32_32x32x16_bf16 v[18:33], v[130:133], v[212:215], v[18:33]
	v_sub_f32_e32 v76, v76, v153
	v_sub_f32_e32 v77, v77, v153
	v_exp_f32_e32 v246, v72
	v_exp_f32_e32 v247, v73
	s_add_i32 s9, s6, 0
	v_add_u32_e32 v130, s9, v164
	s_waitcnt vmcnt(0)
	s_waitcnt vmcnt(4)
	ds_write_b128 v130, v[192:195]
	v_add_u32_e32 v130, s9, v165
	s_waitcnt vmcnt(2)
	ds_write_b128 v130, v[200:203]
	v_add_u32_e32 v130, s9, v167
	v_mfma_f32_32x32x16_bf16 v[18:33], v[154:157], v[216:219], v[18:33]
	ds_write_b128 v130, v[196:199] offset:16384
	v_add_u32_e32 v130, s9, v168
	s_waitcnt vmcnt(1)
	ds_write_b128 v130, v[204:207] offset:16384
	v_add_u32_e32 v130, s9, v169
	v_cmp_gt_f32_e32 vcc, 1.0, v152
	s_waitcnt vmcnt(0)
	ds_write_b128 v130, v[208:211] offset:32768
	v_sub_f32_e32 v78, v78, v153
	v_sub_f32_e32 v79, v79, v153
	v_exp_f32_e32 v248, v74
	v_exp_f32_e32 v249, v75
	v_mfma_f32_32x32x16_bf16 v[18:33], v[184:187], v[220:223], v[18:33]
	v_sub_f32_e32 v80, v80, v153
	v_sub_f32_e32 v81, v81, v153
	v_exp_f32_e32 v250, v76
	v_exp_f32_e32 v251, v77
	v_mfma_f32_32x32x16_bf16 v[18:33], v[188:191], v[228:231], v[18:33]
	v_exp_f32_e32 v252, v78
	v_exp_f32_e32 v253, v79
	v_exp_f32_e32 v254, v80
	v_exp_f32_e32 v255, v81
	s_cbranch_vccz .LBB0_669
; #define MFMA32(a, b, c) __builtin_amdgcn_mfma_f32_32x32x16_bf16((a), (b), (c), 0, 0, 0)
; DI void a_qkt(f32x16& p0, f32x16& p1, const char* Ks, const char* Ps, const bf16x8* qr, const char* QP, int r32, int hi) {
;   p0 = f32x16{}; p1 = f32x16{};
; #pragma unroll
;   for (int d0 = 0; d0 < 8; ++d0) { const int cb = (d0 * 16 + hi * 8) * 2;
;     bf16x8 b0 = *reinterpret_cast<const bf16x8*>(Ks + KSWZ(r32, cb));
;     bf16x8 b1 = *reinterpret_cast<const bf16x8*>(Ks + KSWZ(32 + r32, cb));
;     p0 = MFMA32(b0, qr[d0], p0);
;     p1 = MFMA32(b1, qr[d0], p1); }
; #pragma unroll
;   for (int d0 = 0; d0 < 4; ++d0) { const int cb = (d0 * 16 + hi * 8) * 2;
;     bf16x8 b0 = *reinterpret_cast<const bf16x8*>(Ps + PSWZ(r32, cb));
;     bf16x8 b1 = *reinterpret_cast<const bf16x8*>(Ps + PSWZ(32 + r32, cb));
;     const bf16x8 qp = *reinterpret_cast<const bf16x8*>(QP + d0 * 1024);
;     p0 = MFMA32(b0, qp, p0);
;     p1 = MFMA32(b1, qp, p1); }
; }
	s_and_saveexec_b64 s[4:5], s[2:3]
	ds_write_b32 v161, v152 offset:128
	s_or_b64 exec, exec, s[4:5]
	s_waitcnt lgkmcnt(0)
	v_add_u32_e32 v144, v137, v134
	ds_read_b128 v[130:133], v144 offset:224
	ds_read_b128 v[154:157], v144 offset:192
	ds_read_b128 v[184:187], v144 offset:160
	ds_read_b128 v[188:191], v144 offset:128
	s_waitcnt lgkmcnt(3)
	v_pk_mul_f32 v[14:15], v[14:15], v[130:131]
	s_waitcnt lgkmcnt(2)
	v_pk_mul_f32 v[10:11], v[10:11], v[154:155]
	s_waitcnt lgkmcnt(1)
	v_pk_mul_f32 v[6:7], v[6:7], v[184:185]
	v_pk_mul_f32 v[16:17], v[16:17], v[132:133]
	v_pk_mul_f32 v[12:13], v[12:13], v[156:157]
	v_pk_mul_f32 v[8:9], v[8:9], v[186:187]
	s_waitcnt lgkmcnt(0)
	v_pk_mul_f32 v[4:5], v[4:5], v[190:191]
	v_pk_mul_f32 v[2:3], v[2:3], v[188:189]
	v_pk_mul_f32 v[62:63], v[62:63], v[130:131]
	v_pk_mul_f32 v[58:59], v[58:59], v[154:155]
	v_pk_mul_f32 v[54:55], v[54:55], v[184:185]
	v_pk_mul_f32 v[64:65], v[64:65], v[132:133]
	v_pk_mul_f32 v[60:61], v[60:61], v[156:157]
	v_pk_mul_f32 v[56:57], v[56:57], v[186:187]
	v_pk_mul_f32 v[52:53], v[52:53], v[190:191]
	v_pk_mul_f32 v[50:51], v[50:51], v[188:189]
	v_pk_mul_f32 v[46:47], v[46:47], v[130:131]
	v_pk_mul_f32 v[42:43], v[42:43], v[154:155]
	v_pk_mul_f32 v[38:39], v[38:39], v[184:185]
	v_pk_mul_f32 v[48:49], v[48:49], v[132:133]
	v_pk_mul_f32 v[44:45], v[44:45], v[156:157]
	v_pk_mul_f32 v[40:41], v[40:41], v[186:187]
	v_pk_mul_f32 v[36:37], v[36:37], v[190:191]
	v_pk_mul_f32 v[34:35], v[34:35], v[188:189]
	v_pk_mul_f32 v[30:31], v[30:31], v[130:131]
	v_pk_mul_f32 v[26:27], v[26:27], v[154:155]
	v_pk_mul_f32 v[22:23], v[22:23], v[184:185]
	v_pk_mul_f32 v[32:33], v[32:33], v[132:133]
	v_pk_mul_f32 v[28:29], v[28:29], v[156:157]
	v_pk_mul_f32 v[24:25], v[24:25], v[186:187]
	v_pk_mul_f32 v[20:21], v[20:21], v[190:191]
	v_pk_mul_f32 v[18:19], v[18:19], v[188:189]
.LBB0_669:
	s_waitcnt lgkmcnt(0)
	s_barrier
	v_add_u32_e32 v70, s9, v170
	ds_read_b128 v[66:69], v70 offset:16384
	ds_read_b128 v[70:73], v70 offset:24576
	v_add_u32_e32 v226, s9, v172
	ds_read_b128 v[204:207], v226 offset:16384
	ds_read_b128 v[208:211], v226 offset:24576
	v_sub_f32_e32 v144, v82, v153
	v_sub_f32_e32 v188, v83, v153
	v_sub_f32_e32 v189, v84, v153
	v_sub_f32_e32 v190, v85, v153
	v_sub_f32_e32 v191, v86, v153
	v_sub_f32_e32 v192, v87, v153
	v_sub_f32_e32 v193, v88, v153
	v_sub_f32_e32 v194, v89, v153
	v_sub_f32_e32 v195, v90, v153
	v_sub_f32_e32 v196, v91, v153
	v_sub_f32_e32 v197, v92, v153
	v_sub_f32_e32 v198, v93, v153
	v_sub_f32_e32 v199, v94, v153
	v_sub_f32_e32 v200, v95, v153
	v_sub_f32_e32 v201, v96, v153
	v_sub_f32_e32 v202, v97, v153
	s_waitcnt lgkmcnt(3)
	v_mfma_f32_32x32x16_bf16 v[82:97], v[66:69], v[114:117], 0
	v_exp_f32_e32 v144, v144
	v_exp_f32_e32 v156, v188
	s_waitcnt lgkmcnt(2)
	v_mfma_f32_32x32x16_bf16 v[66:81], v[70:73], v[114:117], 0
	v_add_u32_e32 v226, s9, v173
	ds_read_b128 v[216:219], v226 offset:16384
	ds_read_b128 v[220:223], v226 offset:24576
	v_exp_f32_e32 v157, v189
	v_exp_f32_e32 v184, v190
	s_waitcnt lgkmcnt(3)
	v_mfma_f32_32x32x16_bf16 v[82:97], v[204:207], v[118:121], v[82:97]
	v_exp_f32_e32 v185, v191
	v_exp_f32_e32 v192, v192
	s_waitcnt lgkmcnt(2)
	v_mfma_f32_32x32x16_bf16 v[66:81], v[208:211], v[118:121], v[66:81]
	v_add_u32_e32 v226, s9, v174
	ds_read_b128 v[204:207], v226 offset:16384
	ds_read_b128 v[208:211], v226 offset:24576
	v_exp_f32_e32 v193, v193
	v_exp_f32_e32 v194, v194
	s_waitcnt lgkmcnt(3)
	v_mfma_f32_32x32x16_bf16 v[82:97], v[216:219], v[126:129], v[82:97]
	v_exp_f32_e32 v195, v195
	v_add_f32_e32 v203, 0, v240
	v_add_f32_e32 v203, v241, v203
	s_waitcnt lgkmcnt(2)
	v_mfma_f32_32x32x16_bf16 v[66:81], v[220:223], v[126:129], v[66:81]
	v_add_u32_e32 v226, s9, v175
	ds_read_b128 v[216:219], v226 offset:16384
	ds_read_b128 v[220:223], v226 offset:24576
	v_exp_f32_e32 v196, v196
	v_add_f32_e32 v203, v242, v203
	v_add_f32_e32 v203, v243, v203
	s_waitcnt lgkmcnt(3)
	v_mfma_f32_32x32x16_bf16 v[82:97], v[204:207], v[122:125], v[82:97]
	v_exp_f32_e32 v197, v197
	v_add_f32_e32 v203, v244, v203
	v_add_f32_e32 v203, v245, v203
	s_waitcnt lgkmcnt(2)
	v_mfma_f32_32x32x16_bf16 v[66:81], v[208:211], v[122:125], v[66:81]
	v_add_u32_e32 v226, s9, v176
	ds_read_b128 v[204:207], v226 offset:16384
	ds_read_b128 v[208:211], v226 offset:24576
	v_exp_f32_e32 v198, v198
	v_add_f32_e32 v203, v246, v203
	v_add_f32_e32 v203, v247, v203
	s_waitcnt lgkmcnt(3)
	v_mfma_f32_32x32x16_bf16 v[82:97], v[216:219], v[110:113], v[82:97]
	v_exp_f32_e32 v199, v199
	v_add_f32_e32 v203, v248, v203
	v_add_f32_e32 v203, v249, v203
	s_waitcnt lgkmcnt(2)
	v_mfma_f32_32x32x16_bf16 v[66:81], v[220:223], v[110:113], v[66:81]
	v_add_u32_e32 v226, s9, v177
	ds_read_b128 v[216:219], v226 offset:16384
	ds_read_b128 v[220:223], v226 offset:24576
	v_exp_f32_e32 v200, v200
	v_add_f32_e32 v203, v250, v203
	v_add_f32_e32 v203, v251, v203
	s_waitcnt lgkmcnt(3)
	v_mfma_f32_32x32x16_bf16 v[82:97], v[204:207], v[106:109], v[82:97]
	v_exp_f32_e32 v201, v201
	v_add_f32_e32 v203, v252, v203
	v_add_f32_e32 v203, v253, v203
	s_waitcnt lgkmcnt(2)
	v_mfma_f32_32x32x16_bf16 v[66:81], v[208:211], v[106:109], v[66:81]
	v_add_u32_e32 v226, s9, v178
	ds_read_b128 v[204:207], v226 offset:16384
	ds_read_b128 v[208:211], v226 offset:24576
	v_exp_f32_e32 v202, v202
	v_add_f32_e32 v203, v254, v203
	v_add_f32_e32 v203, v255, v203
	s_waitcnt lgkmcnt(3)
	v_mfma_f32_32x32x16_bf16 v[82:97], v[216:219], v[102:105], v[82:97]
	v_add_f32_e32 v203, v144, v203
	v_add_f32_e32 v203, v156, v203
	v_cvt_pk_bf16_f32 v130, v240, v241
	s_waitcnt lgkmcnt(2)
; #define MFMA32(a, b, c) __builtin_amdgcn_mfma_f32_32x32x16_bf16((a), (b), (c), 0, 0, 0)
; DI void a_qkt(f32x16& p0, f32x16& p1, const char* Ks, const char* Ps, const bf16x8* qr, const char* QP, int r32, int hi) {
;   p0 = f32x16{}; p1 = f32x16{};
; #pragma unroll
;   for (int d0 = 0; d0 < 8; ++d0) { const int cb = (d0 * 16 + hi * 8) * 2;
;     bf16x8 b0 = *reinterpret_cast<const bf16x8*>(Ks + KSWZ(r32, cb));
;     bf16x8 b1 = *reinterpret_cast<const bf16x8*>(Ks + KSWZ(32 + r32, cb));
;     p0 = MFMA32(b0, qr[d0], p0);
;     p1 = MFMA32(b1, qr[d0], p1); }
; #pragma unroll
;   for (int d0 = 0; d0 < 4; ++d0) { const int cb = (d0 * 16 + hi * 8) * 2;
;     bf16x8 b0 = *reinterpret_cast<const bf16x8*>(Ps + PSWZ(r32, cb));
;     bf16x8 b1 = *reinterpret_cast<const bf16x8*>(Ps + PSWZ(32 + r32, cb));
;     const bf16x8 qp = *reinterpret_cast<const bf16x8*>(QP + d0 * 1024);
;     p0 = MFMA32(b0, qp, p0);
;     p1 = MFMA32(b1, qp, p1); }
; }
; DI void pv_sm(f32x16* o, int vb, bf16x8 pa0, bf16x8 pa1, bf16x8 pa2, bf16x8 pa3, f32x16& p0, f32x16& p1, float& m_reg, float& mn, float& alpha) {
;   PV_BLOCK(0)
;   float pm0 = p0[0];
; #pragma unroll
;   for (int r = 1; r < 16; ++r) pm0 = fmaxf(pm0, p0[r]);
;   PV_BLOCK(1)
;   float pmax = pm0;
; #pragma unroll
;   for (int r = 0; r < 16; ++r) pmax = fmaxf(pmax, p1[r]);
	v_mfma_f32_32x32x16_bf16 v[66:81], v[220:223], v[102:105], v[66:81]
	v_add_u32_e32 v226, s9, v179
	ds_read_b128 v[216:219], v226 offset:32768
	ds_read_b128 v[220:223], v226 offset:36864
	ds_read_b128 v[228:231], v163
	v_add_f32_e32 v203, v157, v203
	v_add_f32_e32 v203, v184, v203
	v_cvt_pk_bf16_f32 v131, v242, v243
	s_waitcnt lgkmcnt(4)
	v_mfma_f32_32x32x16_bf16 v[82:97], v[204:207], v[98:101], v[82:97]
	v_add_f32_e32 v203, v185, v203
	v_add_f32_e32 v203, v192, v203
	v_cvt_pk_bf16_f32 v132, v244, v245
	s_waitcnt lgkmcnt(3)
	v_mfma_f32_32x32x16_bf16 v[66:81], v[208:211], v[98:101], v[66:81]
	v_add_u32_e32 v226, s9, v180
	ds_read_b128 v[204:207], v226 offset:32768
	ds_read_b128 v[208:211], v226 offset:36864
	ds_read_b128 v[212:215], v163 offset:1024
	v_add_f32_e32 v203, v193, v203
	v_add_f32_e32 v203, v194, v203
	v_cvt_pk_bf16_f32 v133, v246, v247
	s_waitcnt lgkmcnt(3)
	v_mfma_f32_32x32x16_bf16 v[82:97], v[216:219], v[228:231], v[82:97]
	v_add_f32_e32 v203, v195, v203
	v_add_f32_e32 v203, v196, v203
	v_cvt_pk_bf16_f32 v186, v248, v249
	v_mfma_f32_32x32x16_bf16 v[66:81], v[220:223], v[228:231], v[66:81]
	v_add_u32_e32 v226, s9, v181
	ds_read_b128 v[216:219], v226 offset:32768
	ds_read_b128 v[220:223], v226 offset:36864
	ds_read_b128 v[228:231], v163 offset:2048
	v_add_f32_e32 v203, v197, v203
	v_add_f32_e32 v203, v198, v203
	v_cvt_pk_bf16_f32 v187, v250, v251
	s_waitcnt lgkmcnt(3)
	v_mfma_f32_32x32x16_bf16 v[82:97], v[204:207], v[212:215], v[82:97]
	v_add_f32_e32 v203, v199, v203
	v_add_f32_e32 v203, v200, v203
	v_cvt_pk_bf16_f32 v188, v252, v253
	v_mfma_f32_32x32x16_bf16 v[66:81], v[208:211], v[212:215], v[66:81]
	v_add_u32_e32 v226, s9, v182
	ds_read_b128 v[204:207], v226 offset:32768
	ds_read_b128 v[208:211], v226 offset:36864
	ds_read_b128 v[212:215], v163 offset:3072
	v_add_f32_e32 v203, v201, v203
	v_add_f32_e32 v154, v202, v203
	v_cvt_pk_bf16_f32 v189, v254, v255
	s_waitcnt lgkmcnt(3)
	v_mfma_f32_32x32x16_bf16 v[82:97], v[216:219], v[228:231], v[82:97]
	v_mov_b32_e32 v155, v154
	v_cvt_pk_bf16_f32 v190, v144, v156
	v_cvt_pk_bf16_f32 v191, v157, v184
	v_permlane32_swap_b32_e32 v130, v132
	v_mfma_f32_32x32x16_bf16 v[66:81], v[220:223], v[228:231], v[66:81]
	v_add_u32_e32 v232, s7, v171
	ds_read_b64_tr_b16 v[216:217], v232 offset:2048
	ds_read_b64_tr_b16 v[218:219], v232 offset:4096
	ds_read_b64_tr_b16 v[220:221], v232 offset:6144
	ds_read_b64_tr_b16 v[222:223], v232 offset:8192
	ds_read_b64_tr_b16 v[224:225], v232 offset:10240
	ds_read_b64_tr_b16 v[226:227], v232 offset:12288
	ds_read_b64_tr_b16 v[228:229], v232 offset:14336
	v_cvt_pk_bf16_f32 v192, v185, v192
	v_cvt_pk_bf16_f32 v193, v193, v194
	v_permlane32_swap_b32_e32 v154, v155
	v_permlane32_swap_b32_e32 v131, v133
	s_waitcnt lgkmcnt(7)
	v_mfma_f32_32x32x16_bf16 v[82:97], v[204:207], v[212:215], v[82:97]
	v_cvt_pk_bf16_f32 v194, v195, v196
	v_cvt_pk_bf16_f32 v195, v197, v198
	v_permlane32_swap_b32_e32 v186, v188
	v_mfma_f32_32x32x16_bf16 v[66:81], v[208:211], v[212:215], v[66:81]
	ds_read_b64_tr_b16 v[214:215], v232 offset:0
	v_cvt_pk_bf16_f32 v196, v199, v200
	v_cvt_pk_bf16_f32 v197, v201, v202
	v_permlane32_swap_b32_e32 v187, v189
	s_nop 0
	v_permlane32_swap_b32_e32 v190, v192
	v_permlane32_swap_b32_e32 v191, v193
	v_permlane32_swap_b32_e32 v194, v196
	v_permlane32_swap_b32_e32 v195, v197
	v_add_co_u32_e32 v156, vcc, s59, v146
	s_nop 1
	v_addc_co_u32_e32 v157, vcc, 0, v147, vcc
	v_add_co_u32_e32 v146, vcc, s60, v146
	s_nop 1
	v_addc_co_u32_e32 v147, vcc, 0, v147, vcc
	global_load_dwordx4 v[198:201], v[156:157], off offset:256
	global_load_dwordx4 v[202:205], v[156:157], off
	global_load_dwordx4 v[206:209], v[146:147], off offset:256
	global_load_dwordx4 v[210:213], v[146:147], off
	v_add_co_u32_e32 v146, vcc, s61, v148
	s_nop 1
	v_addc_co_u32_e32 v147, vcc, 0, v149, vcc
	global_load_dwordx4 v[146:149], v[146:147], off
	v_add_u32_e32 v156, s7, v171
	s_waitcnt lgkmcnt(0)
	s_nop 0
	v_mfma_f32_32x32x16_bf16 v[2:17], v[130:133], v[214:217], v[2:17]
	ds_read_b64_tr_b16 v[214:215], v156 offset:0x200
	ds_read_b64_tr_b16 v[216:217], v156 offset:0xa00
	v_max_f32_e32 v144, v83, v83
	v_max_f32_e32 v157, v82, v82
	v_max_f32_e32 v144, v157, v144
	v_max3_f32 v144, v144, v84, v85
	v_max3_f32 v144, v144, v86, v87
	v_mfma_f32_32x32x16_bf16 v[2:17], v[186:189], v[218:221], v[2:17]
	ds_read_b64_tr_b16 v[218:219], v156 offset:0x1200
	ds_read_b64_tr_b16 v[220:221], v156 offset:0x1a00
	v_max3_f32 v144, v144, v88, v89
	v_max3_f32 v144, v144, v90, v91
	v_max3_f32 v144, v144, v92, v93
	v_max3_f32 v144, v144, v94, v95
	v_max3_f32 v144, v144, v96, v97
	v_mfma_f32_32x32x16_bf16 v[2:17], v[190:193], v[222:225], v[2:17]
	ds_read_b64_tr_b16 v[222:223], v156 offset:0x2200
	ds_read_b64_tr_b16 v[224:225], v156 offset:0x2a00
	ds_read_b64_tr_b16 v[230:231], v156 offset:0x3200
	ds_read_b64_tr_b16 v[232:233], v156 offset:0x3a00
	v_mfma_f32_32x32x16_bf16 v[2:17], v[194:197], v[226:229], v[2:17]
	s_waitcnt lgkmcnt(0)
; DI void pv_sm(f32x16* o, int vb, bf16x8 pa0, bf16x8 pa1, bf16x8 pa2, bf16x8 pa3, f32x16& p0, f32x16& p1, float& m_reg, float& mn, float& alpha) {
;   PV_BLOCK(0)
;   float pm0 = p0[0];
; #pragma unroll
;   for (int r = 1; r < 16; ++r) pm0 = fmaxf(pm0, p0[r]);
;   PV_BLOCK(1)
;   float pmax = pm0;
; #pragma unroll
;   for (int r = 0; r < 16; ++r) pmax = fmaxf(pmax, p1[r]);
;   { auto rr = __builtin_amdgcn_permlane32_swap(__float_as_uint(pmax), __float_as_uint(pmax), false, false);
;     pmax = fmaxf(__uint_as_float(rr[0]), __uint_as_float(rr[1])); }
;   const bool keep = __all(pmax - m_reg <= ATH);
;   mn = keep ? m_reg : fmaxf(m_reg, pmax);
;   alpha = __builtin_amdgcn_exp2f(m_reg - mn);
;   m_reg = mn;
;   PV_BLOCK(2)
; #pragma unroll
;   for (int r = 0; r < 16; ++r) { p0[r] = p0[r] - mn; p1[r] = p1[r] - mn; }
;   PV_BLOCK(3)
; #pragma unroll
;   for (int r = 0; r < 16; ++r) p0[r] = __builtin_amdgcn_exp2f(p0[r]);
; }
	v_mfma_f32_32x32x16_bf16 v[50:65], v[130:133], v[214:217], v[50:65]
	v_max3_f32 v144, v144, v66, v67
	v_max3_f32 v144, v144, v68, v69
	v_max3_f32 v144, v144, v70, v71
	v_max3_f32 v144, v144, v72, v73
	v_max3_f32 v144, v144, v74, v75
	v_max3_f32 v144, v144, v76, v77
	v_max3_f32 v144, v144, v78, v79
	v_mfma_f32_32x32x16_bf16 v[50:65], v[186:189], v[218:221], v[50:65]
	v_max3_f32 v144, v144, v80, v81
	v_mov_b32_e32 v157, v144
	s_nop 1
	v_permlane32_swap_b32_e32 v144, v157
	v_max_f32_e32 v157, v157, v157
	v_max_f32_e32 v144, v144, v144
	v_max_f32_e32 v144, v144, v157
	v_mfma_f32_32x32x16_bf16 v[50:65], v[190:193], v[222:225], v[50:65]
	ds_read_b64_tr_b16 v[214:215], v156 offset:0x400
	v_sub_f32_e32 v157, v144, v153
	ds_read_b64_tr_b16 v[216:217], v156 offset:0xc00
	v_cmp_ge_f32_e32 vcc, s54, v157
	ds_read_b64_tr_b16 v[218:219], v156 offset:0x1400
	s_cmp_eq_u64 vcc, exec
	v_max_f32_e32 v157, v153, v153
	ds_read_b64_tr_b16 v[220:221], v156 offset:0x1c00
	ds_read_b64_tr_b16 v[222:223], v156 offset:0x2400
	ds_read_b64_tr_b16 v[224:225], v156 offset:0x2c00
	ds_read_b64_tr_b16 v[226:227], v156 offset:0x3400
	ds_read_b64_tr_b16 v[228:229], v156 offset:0x3c00
	v_mfma_f32_32x32x16_bf16 v[50:65], v[194:197], v[230:233], v[50:65]
	v_max_f32_e32 v144, v157, v144
	s_cselect_b64 vcc, -1, 0
	v_cndmask_b32_e32 v144, v144, v153, vcc
	v_sub_f32_e32 v153, v153, v144
	v_exp_f32_e32 v184, v153
	s_waitcnt lgkmcnt(0)
	v_mfma_f32_32x32x16_bf16 v[34:49], v[130:133], v[214:217], v[34:49]
	ds_read_b64_tr_b16 v[214:215], v156 offset:0x600
	ds_read_b64_tr_b16 v[216:217], v156 offset:0xe00
	v_sub_f32_e32 v82, v82, v144
	v_sub_f32_e32 v83, v83, v144
	v_sub_f32_e32 v84, v84, v144
	v_sub_f32_e32 v85, v85, v144
	v_mfma_f32_32x32x16_bf16 v[34:49], v[186:189], v[218:221], v[34:49]
	ds_read_b64_tr_b16 v[218:219], v156 offset:0x1600
	ds_read_b64_tr_b16 v[220:221], v156 offset:0x1e00
	v_sub_f32_e32 v86, v86, v144
	v_sub_f32_e32 v87, v87, v144
	v_exp_f32_e32 v240, v82
	v_exp_f32_e32 v241, v83
	v_mfma_f32_32x32x16_bf16 v[34:49], v[190:193], v[222:225], v[34:49]
	ds_read_b64_tr_b16 v[222:223], v156 offset:0x2600
	ds_read_b64_tr_b16 v[224:225], v156 offset:0x2e00
	ds_read_b64_tr_b16 v[230:231], v156 offset:0x3600
	ds_read_b64_tr_b16 v[232:233], v156 offset:0x3e00
	v_mfma_f32_32x32x16_bf16 v[34:49], v[194:197], v[226:229], v[34:49]
	v_sub_f32_e32 v88, v88, v144
	v_sub_f32_e32 v89, v89, v144
	v_exp_f32_e32 v242, v84
	v_exp_f32_e32 v243, v85
	s_waitcnt lgkmcnt(0)
	v_sub_f32_e32 v90, v90, v144
	v_sub_f32_e32 v91, v91, v144
	v_exp_f32_e32 v244, v86
	v_exp_f32_e32 v245, v87
	v_mfma_f32_32x32x16_bf16 v[18:33], v[130:133], v[214:217], v[18:33]
	v_sub_f32_e32 v92, v92, v144
	v_sub_f32_e32 v93, v93, v144
	v_exp_f32_e32 v246, v88
	v_exp_f32_e32 v247, v89
	s_add_i32 s9, s8, 0
	v_add_u32_e32 v130, s9, v164
	s_waitcnt vmcnt(0)
	s_waitcnt vmcnt(4)
	ds_write_b128 v130, v[198:201]
	v_add_u32_e32 v130, s9, v165
	s_waitcnt vmcnt(2)
	ds_write_b128 v130, v[206:209]
	v_add_u32_e32 v130, s9, v167
	v_mfma_f32_32x32x16_bf16 v[18:33], v[186:189], v[218:221], v[18:33]
	ds_write_b128 v130, v[202:205] offset:16384
	v_add_u32_e32 v130, s9, v168
	s_waitcnt vmcnt(1)
	ds_write_b128 v130, v[210:213] offset:16384
	v_add_u32_e32 v130, s9, v169
	v_cmp_gt_f32_e32 vcc, 1.0, v184
	s_waitcnt vmcnt(0)
	ds_write_b128 v130, v[146:149] offset:32768
	v_sub_f32_e32 v94, v94, v144
	v_sub_f32_e32 v95, v95, v144
	v_exp_f32_e32 v248, v90
	v_exp_f32_e32 v249, v91
	v_mfma_f32_32x32x16_bf16 v[18:33], v[190:193], v[222:225], v[18:33]
	v_sub_f32_e32 v96, v96, v144
	v_sub_f32_e32 v97, v97, v144
	v_exp_f32_e32 v250, v92
	v_exp_f32_e32 v251, v93
	v_mfma_f32_32x32x16_bf16 v[18:33], v[194:197], v[230:233], v[18:33]
	v_exp_f32_e32 v252, v94
	v_exp_f32_e32 v253, v95
	v_exp_f32_e32 v254, v96
	v_exp_f32_e32 v255, v97
	s_cbranch_vccz .LBB0_673
	s_and_saveexec_b64 s[4:5], s[2:3]
	ds_write_b32 v161, v184 offset:128
	s_or_b64 exec, exec, s[4:5]
	s_waitcnt lgkmcnt(0)
	v_add_u32_e32 v153, v137, v134
	ds_read_b128 v[130:133], v153 offset:224
	ds_read_b128 v[146:149], v153 offset:192
	ds_read_b128 v[186:189], v153 offset:160
	ds_read_b128 v[190:193], v153 offset:128
	s_waitcnt lgkmcnt(3)
	v_pk_mul_f32 v[14:15], v[14:15], v[130:131]
	s_waitcnt lgkmcnt(2)
	v_pk_mul_f32 v[10:11], v[10:11], v[146:147]
	s_waitcnt lgkmcnt(1)
	v_pk_mul_f32 v[6:7], v[6:7], v[186:187]
	v_pk_mul_f32 v[16:17], v[16:17], v[132:133]
	v_pk_mul_f32 v[12:13], v[12:13], v[148:149]
	v_pk_mul_f32 v[8:9], v[8:9], v[188:189]
	s_waitcnt lgkmcnt(0)
	v_pk_mul_f32 v[4:5], v[4:5], v[192:193]
	v_pk_mul_f32 v[2:3], v[2:3], v[190:191]
	v_pk_mul_f32 v[62:63], v[62:63], v[130:131]
	v_pk_mul_f32 v[58:59], v[58:59], v[146:147]
	v_pk_mul_f32 v[54:55], v[54:55], v[186:187]
	v_pk_mul_f32 v[64:65], v[64:65], v[132:133]
	v_pk_mul_f32 v[60:61], v[60:61], v[148:149]
	v_pk_mul_f32 v[56:57], v[56:57], v[188:189]
	v_pk_mul_f32 v[52:53], v[52:53], v[192:193]
	v_pk_mul_f32 v[50:51], v[50:51], v[190:191]
	v_pk_mul_f32 v[46:47], v[46:47], v[130:131]
	v_pk_mul_f32 v[42:43], v[42:43], v[146:147]
	v_pk_mul_f32 v[38:39], v[38:39], v[186:187]
	v_pk_mul_f32 v[48:49], v[48:49], v[132:133]
	v_pk_mul_f32 v[44:45], v[44:45], v[148:149]
	v_pk_mul_f32 v[40:41], v[40:41], v[188:189]
	v_pk_mul_f32 v[36:37], v[36:37], v[192:193]
	v_pk_mul_f32 v[34:35], v[34:35], v[190:191]
	v_pk_mul_f32 v[30:31], v[30:31], v[130:131]
	v_pk_mul_f32 v[26:27], v[26:27], v[146:147]
	v_pk_mul_f32 v[22:23], v[22:23], v[186:187]
	v_pk_mul_f32 v[32:33], v[32:33], v[132:133]
	v_pk_mul_f32 v[28:29], v[28:29], v[148:149]
	v_pk_mul_f32 v[24:25], v[24:25], v[188:189]
	v_pk_mul_f32 v[20:21], v[20:21], v[192:193]
	v_pk_mul_f32 v[18:19], v[18:19], v[190:191]
